# speedup vs baseline: 1.0026x; 1.0026x over previous
; template <int DQK, int DV, int MODE> ...
;     ...
;     bf16x8 qf[DQK / 16];
;     { const bf16_t* qp = Qb + (size_t)(qrow_base + wid * 32 + r) * QS + qcol0 + h * 8;
; #pragma unroll
;       for (int d0 = 0; d0 < DQK / 16; ++d0) qf[d0] = *(const bf16x8*)(qp + d0 * 16); }
;     u32x4 kreg[NKL], vreg[NVL];
;     const unsigned g_off0 = (MODE == 2) ? (unsigned)((tid >> 3) * NIN1 * 2 + (tid & 7) * 16) : (unsigned)((tid >> 4) * NKV * 2 + (tid & 15) * 16);
;     const unsigned g_offr = (unsigned)((tid >> 3) * NIN0 * 2 + (tid & 7) * 16);
;     const unsigned l_k0 = (MODE == 2) ? (unsigned)((tid >> 3) * KS + (tid & 7) * 16) : (unsigned)((tid >> 4) * KS + (tid & 15) * 16);
;     const unsigned l_kr = (unsigned)((tid >> 3) * KS + 256 + (tid & 7) * 16);
;     const unsigned l_v0 = (MODE == 2) ? (unsigned)(KBYTES + (tid >> 3) * VS + (tid & 7) * 16) : (unsigned)(KBYTES + (tid >> 4) * VS + (tid & 15) * 16);
;     ...
;     f32x16 o[DV / 32];
; #pragma unroll
;     for (int d = 0; d < DV / 32; ++d)
; #pragma unroll
;         for (int e = 0; e < 16; ++e) o[d][e] = 0.f;
;     float m = (MODE == 2) ? sink2 : -1e30f, l = (MODE == 2) ? 0.5f : 0.f;
;     const int qa = q0 + wid * 32;
;     const int vlane = (4 * h + ((lane & 15) >> 2)) * VS + (16 * ((lane >> 4) & 1) + 4 * (lane & 3)) * 2;
;     FL_LOAD(0); FL_STORE(0); __syncthreads();
;     if (wid >= 4) __builtin_amdgcn_s_setprio(1);
.LBB0_594:
	s_and_b64 s[6:7], s[26:27], exec
	s_cselect_b32 s0, s70, s58
	s_and_b32 s58, s0, 7
	s_lshr_b32 s0, s71, 1
	s_and_b32 s59, s0, 0x7fffffe0
	s_add_u32 s26, s54, s59
	s_addc_u32 s27, s55, 0
	v_lshl_add_u64 v[0:1], s[26:27], 0, v[166:167]
	v_mov_b64_e32 v[2:3], s[14:15]
	v_mad_u64_u32 v[2:3], s[6:7], v0, s68, v[2:3]
	v_mov_b32_e32 v0, v3
	v_mad_u64_u32 v[0:1], s[6:7], v1, s68, v[0:1]
	v_mov_b32_e32 v3, v0
	s_mul_i32 s0, s58, 0x180
	v_lshl_add_u64 v[0:1], v[2:3], 0, s[0:1]
	v_lshl_add_u64 v[20:21], v[0:1], 0, v[168:169]
	s_lshl_b64 s[6:7], s[44:45], 12
	global_load_dwordx4 v[160:163], v[20:21], off
	global_load_dwordx4 v[156:159], v[20:21], off offset:32
	global_load_dwordx4 v[152:155], v[20:21], off offset:64
	global_load_dwordx4 v[148:151], v[20:21], off offset:96
	global_load_dwordx4 v[140:143], v[20:21], off offset:128
	global_load_dwordx4 v[132:135], v[20:21], off offset:160
	global_load_dwordx4 v[124:127], v[20:21], off offset:192
	global_load_dwordx4 v[116:119], v[20:21], off offset:224
	s_add_u32 s0, s16, s6
	s_addc_u32 s7, s17, s7
	s_lshl_b32 s6, s58, 9
	s_add_u32 s6, s0, s6
	s_addc_u32 s7, s7, 0
	v_lshl_add_u64 v[12:13], s[6:7], 0, v[170:171]
	v_add_co_u32_e32 v4, vcc, s69, v12
	global_load_dwordx4 v[0:3], v[12:13], off
	s_nop 0
	v_addc_co_u32_e32 v5, vcc, 0, v13, vcc
	global_load_dwordx4 v[4:7], v[4:5], off
	v_mad_u64_u32 v[8:9], s[6:7], s44, v218, v[204:205]
	s_mul_i32 s0, s45, 0x1a00
	v_lshl_add_u64 v[16:17], v[12:13], 0, s[4:5]
	v_add_u32_e32 v9, s0, v9
	global_load_dwordx4 v[8:11], v[8:9], off offset:2048
	s_nop 0
	global_load_dwordx4 v[12:15], v[12:13], off offset:256
	s_nop 0
	global_load_dwordx4 v[16:19], v[16:17], off offset:256
	s_nop 0
	global_load_dwordx4 v[144:147], v[20:21], off offset:256
	global_load_dwordx4 v[136:139], v[20:21], off offset:288
	global_load_dwordx4 v[128:131], v[20:21], off offset:320
	global_load_dwordx4 v[120:123], v[20:21], off offset:352
	s_cmpk_lt_u32 s71, 0x100
	v_add_u32_e32 v20, 0, v212
	s_waitcnt vmcnt(0)
	ds_write_b128 v211, v[0:3]
	ds_write_b128 v211, v[4:7] offset:12800
	ds_write_b128 v20, v[8:11] offset:256
	ds_write_b128 v217, v[12:15] offset:25600
	ds_write_b128 v217, v[16:19] offset:35840
	s_waitcnt lgkmcnt(0)
	s_barrier
	s_cbranch_scc1 .LBB0_596
	s_setprio 0

; template <int DQK, int DV, int MODE> ...
;     ...
;     { const bf16_t* qp = Qb + (size_t)(qrow_base + wid * 32 + r) * QS + qcol0 + h * 8;
; #pragma unroll
;       for (int d0 = 0; d0 < DQK / 16; ++d0) qf[d0] = *(const bf16x8*)(qp + d0 * 16); }
;     u32x4 kreg[NKL], vreg[NVL];
;     const unsigned g_off0 = (MODE == 2) ? (unsigned)((tid >> 3) * NIN1 * 2 + (tid & 7) * 16) : (unsigned)((tid >> 4) * NKV * 2 + (tid & 15) * 16);
;     const unsigned g_offr = (unsigned)((tid >> 3) * NIN0 * 2 + (tid & 7) * 16);
;     const unsigned l_k0 = (MODE == 2) ? (unsigned)((tid >> 3) * KS + (tid & 7) * 16) : (unsigned)((tid >> 4) * KS + (tid & 15) * 16);
;     const unsigned l_kr = (unsigned)((tid >> 3) * KS + 256 + (tid & 7) * 16);
;     const unsigned l_v0 = (MODE == 2) ? (unsigned)(KBYTES + (tid >> 3) * VS + (tid & 7) * 16) : (unsigned)(KBYTES + (tid >> 4) * VS + (tid & 15) * 16);
;     ...
;     f32x16 o[DV / 32];
; #pragma unroll
;     for (int d = 0; d < DV / 32; ++d)
; #pragma unroll
;         for (int e = 0; e < 16; ++e) o[d][e] = 0.f;
;     float m = (MODE == 2) ? sink2 : -1e30f, l = (MODE == 2) ? 0.5f : 0.f;
;     const int qa = q0 + wid * 32;
;     const int vlane = (4 * h + ((lane & 15) >> 2)) * VS + (16 * ((lane >> 4) & 1) + 4 * (lane & 3)) * 2;
;     FL_LOAD(0); FL_STORE(0); __syncthreads();
;     if (wid >= 4) __builtin_amdgcn_s_setprio(1);
;     for (int t = 0; t < nt; ++t) {
;         const int buf = t & 1;
;         if (t + 1 < nt) FL_LOAD(t + 1);
.LBB0_1373:
	s_mulk_i32 s5, 0x1400
	s_mul_hi_u32 s6, s4, 0x1400
	s_add_i32 s6, s6, s5
	s_mulk_i32 s4, 0x1400
	s_add_u32 s4, s20, s4
	s_addc_u32 s5, s21, s6
	s_lshl_b32 s6, s27, 4
	s_add_u32 s4, s4, s6
	s_addc_u32 s5, s5, 0
	v_lshl_add_u64 v[2:3], s[4:5], 0, v[76:77]
	v_lshl_add_u64 v[4:5], v[2:3], 0, s[14:15]
	v_add_co_u32_e32 v2, vcc, 0x1000, v2
	s_cmpk_lt_u32 s52, 0x100
	s_nop 0
	v_addc_co_u32_e32 v3, vcc, 0, v3, vcc
	global_load_dwordx4 v[64:67], v[2:3], off
	global_load_dwordx4 v[68:71], v[4:5], off offset:512
	v_add_co_u32_e32 v2, vcc, 0x50000, v2
	s_nop 1
	v_addc_co_u32_e32 v3, vcc, 0, v3, vcc
	v_add_co_u32_e32 v4, vcc, 0x50000, v4
	s_nop 1
	v_addc_co_u32_e32 v5, vcc, 0, v5, vcc
	global_load_dwordx4 v[152:155], v[2:3], off
	global_load_dwordx4 v[156:159], v[4:5], off offset:512
	s_waitcnt vmcnt(2)
	ds_write_b128 v117, v[64:67]
	ds_write_b128 v122, v[68:71] offset:9216
	s_waitcnt lgkmcnt(0)
	s_barrier
	s_cbranch_scc1 .LBB0_1375
	s_setprio 0
